# v42 plus: attention-unit finalize preloads 12 of the 16 attn-norm gain vectors up front and rolls the last 3 through freed registers with counted vmcnt waits, instead of 16 load-wait-store round trips
# baseline (speedup 1.0000x reference)
.LBB0_172:
	s_or_b64 exec, exec, s[2:3]
	global_load_dwordx4 v[64:67], v[102:103], off
	global_load_dwordx4 v[68:71], v[102:103], off offset:32
	global_load_dwordx4 v[72:75], v[102:103], off offset:64
	global_load_dwordx4 v[76:79], v[102:103], off offset:96
	s_waitcnt lgkmcnt(0)
	s_barrier
	ds_read2st64_b32 v[16:17], v152 offset1:1
	ds_read2st64_b32 v[18:19], v152 offset0:2 offset1:3
	v_readlane_b32 s2, v254, 26
	v_readlane_b32 s3, v254, 27
	s_waitcnt lgkmcnt(1)
	v_mov_b32_e32 v20, v16
	s_waitcnt lgkmcnt(0)
	v_mov_b32_e32 v21, v18
	v_mov_b32_e32 v18, v17
	v_pk_add_f32 v[16:17], v[20:21], v[18:19]
	v_lshlrev_b64 v[18:19], 11, v[116:117]
	v_lshl_add_u64 v[18:19], s[2:3], 0, v[18:19]
	v_lshl_add_u64 v[22:23], v[18:19], 0, s[18:19]
	v_add_f32_e32 v16, v16, v17
	v_fmamk_f32 v16, v16, 0x3c000000, v236
	v_cmp_gt_f32_e32 vcc, s39, v16
	v_mul_f32_e32 v17, 0x4b800000, v16
	v_readlane_b32 s2, v254, 3
	v_cndmask_b32_e32 v16, v16, v17, vcc
	v_rsq_f32_e32 v16, v16
	s_add_i32 s37, s37, s2
	v_readlane_b32 s2, v254, 4
	s_add_i32 s7, s7, s2
	v_mul_f32_e32 v17, 0x45800000, v16
	v_cndmask_b32_e32 v16, v16, v17, vcc
	v_pk_mul_f32 v[0:1], v[0:1], v[16:17] op_sel_hi:[1,0]
	v_pk_mul_f32 v[2:3], v[2:3], v[16:17] op_sel_hi:[1,0]
	v_pk_mul_f32 v[4:5], v[4:5], v[16:17] op_sel_hi:[1,0]
	v_readlane_b32 s2, v254, 10
	v_readlane_b32 s3, v254, 11
	s_and_b64 vcc, exec, s[28:29]
	s_waitcnt vmcnt(0)
	v_pk_mul_f32 v[0:1], v[64:65], v[0:1]
	v_lshlrev_b32_e32 v18, 16, v114
	v_and_b32_e32 v19, 0xffff0000, v114
	v_pk_mul_f32 v[0:1], v[0:1], v[18:19]
	v_pk_mul_f32 v[2:3], v[66:67], v[2:3]
	v_lshlrev_b32_e32 v18, 16, v115
	v_and_b32_e32 v19, 0xffff0000, v115
	v_pk_mul_f32 v[2:3], v[2:3], v[18:19]
	v_cvt_pk_bf16_f32 v0, v0, v1
	v_cvt_pk_bf16_f32 v1, v2, v3
	v_lshl_add_u64 v[18:19], v[100:101], 1, v[22:23]
	global_store_dwordx2 v[18:19], v[0:1], off offset:1024
	v_mov_b64_e32 v[0:1], v[68:69]
	v_mov_b64_e32 v[2:3], v[70:71]
	v_lshl_add_u64 v[104:105], v[104:105], 0, s[2:3]
	s_mov_b32 s2, s93
	v_pk_mul_f32 v[0:1], v[0:1], v[4:5]
	v_lshlrev_b32_e32 v4, 16, v112
	v_and_b32_e32 v5, 0xffff0000, v112
	v_pk_mul_f32 v[0:1], v[0:1], v[4:5]
	v_pk_mul_f32 v[4:5], v[6:7], v[16:17] op_sel_hi:[1,0]
	v_cvt_pk_bf16_f32 v0, v0, v1
	v_pk_mul_f32 v[2:3], v[2:3], v[4:5]
	v_lshlrev_b32_e32 v4, 16, v113
	v_and_b32_e32 v5, 0xffff0000, v113
	v_pk_mul_f32 v[2:3], v[2:3], v[4:5]
	v_pk_mul_f32 v[4:5], v[8:9], v[16:17] op_sel_hi:[1,0]
	v_cvt_pk_bf16_f32 v1, v2, v3
	global_store_dwordx2 v[18:19], v[0:1], off offset:1040
	v_mov_b64_e32 v[0:1], v[72:73]
	v_mov_b64_e32 v[2:3], v[74:75]
	v_pk_mul_f32 v[0:1], v[0:1], v[4:5]
	v_lshlrev_b32_e32 v4, 16, v110
	v_and_b32_e32 v5, 0xffff0000, v110
	v_pk_mul_f32 v[0:1], v[0:1], v[4:5]
	v_pk_mul_f32 v[4:5], v[10:11], v[16:17] op_sel_hi:[1,0]
	v_cvt_pk_bf16_f32 v0, v0, v1
	v_pk_mul_f32 v[2:3], v[2:3], v[4:5]
	v_lshlrev_b32_e32 v4, 16, v111
	v_and_b32_e32 v5, 0xffff0000, v111
	v_pk_mul_f32 v[2:3], v[2:3], v[4:5]
	v_pk_mul_f32 v[4:5], v[12:13], v[16:17] op_sel_hi:[1,0]
	v_cvt_pk_bf16_f32 v1, v2, v3
	global_store_dwordx2 v[18:19], v[0:1], off offset:1056
	v_mov_b64_e32 v[0:1], v[76:77]
	v_mov_b64_e32 v[2:3], v[78:79]
	v_pk_mul_f32 v[0:1], v[0:1], v[4:5]
	v_lshlrev_b32_e32 v4, 16, v108
	v_and_b32_e32 v5, 0xffff0000, v108
	v_pk_mul_f32 v[0:1], v[0:1], v[4:5]
	v_pk_mul_f32 v[4:5], v[14:15], v[16:17] op_sel_hi:[1,0]
	v_cvt_pk_bf16_f32 v0, v0, v1
	v_pk_mul_f32 v[2:3], v[2:3], v[4:5]
	v_lshlrev_b32_e32 v4, 16, v109
	v_and_b32_e32 v5, 0xffff0000, v109
	v_pk_mul_f32 v[2:3], v[2:3], v[4:5]
	s_nop 0
	v_cvt_pk_bf16_f32 v1, v2, v3
	global_store_dwordx2 v[18:19], v[0:1], off offset:1072
	s_barrier
	s_cbranch_vccnz .LBB0_183

.LBB0_208:
	s_and_b32 s28, s28, 1
	s_mul_i32 s29, s28, 0x4400
	v_add_u32_e32 v168, s29, v157
	ds_read_b128 v[178:181], v168
	ds_read_b128 v[182:185], v168 offset:8704
	ds_read_b128 v[186:189], v168 offset:32
	ds_read_b128 v[190:193], v168 offset:8736
	ds_read_b128 v[194:197], v168 offset:64
	ds_read_b128 v[198:201], v168 offset:8768
	ds_read_b128 v[202:205], v168 offset:96
	ds_read_b128 v[206:209], v168 offset:8800
	s_add_i32 s29, s27, 0xd9
	v_cmp_lt_u32_e32 vcc, s29, v152
	s_and_b64 vcc, exec, vcc
	s_waitcnt lgkmcnt(7)
	v_mfma_f32_32x32x16_bf16 v[96:111], v[178:181], v[112:115], v[64:79]
	s_waitcnt lgkmcnt(6)
	v_mfma_f32_32x32x16_bf16 v[80:95], v[182:185], v[112:115], v[64:79]
	s_waitcnt lgkmcnt(5)
	v_mfma_f32_32x32x16_bf16 v[96:111], v[186:189], v[116:119], v[96:111]
	s_waitcnt lgkmcnt(4)
	v_mfma_f32_32x32x16_bf16 v[80:95], v[190:193], v[116:119], v[80:95]
	s_waitcnt lgkmcnt(3)
	v_mfma_f32_32x32x16_bf16 v[96:111], v[194:197], v[120:123], v[96:111]
	s_waitcnt lgkmcnt(2)
	v_mfma_f32_32x32x16_bf16 v[80:95], v[198:201], v[120:123], v[80:95]
	s_waitcnt lgkmcnt(1)
	v_mfma_f32_32x32x16_bf16 v[96:111], v[202:205], v[124:127], v[96:111]
	s_waitcnt lgkmcnt(0)
	v_mfma_f32_32x32x16_bf16 v[80:95], v[206:209], v[124:127], v[80:95]
	s_cbranch_vccnz .LBB0_210
	v_add_u32_e32 v168, s27, v176
	v_lshl_add_u32 v177, v168, 2, v159
	ds_read_b32 v178, v177 offset:1024
	ds_read_b32 v179, v177 offset:1028
	ds_read_b32 v180, v177 offset:1032
	ds_read_b32 v181, v177 offset:1036
	ds_read_b32 v182, v177 offset:1056
	ds_read_b32 v183, v177 offset:1060
	ds_read_b32 v184, v177 offset:1064
	ds_read_b32 v185, v177 offset:1068
	ds_read_b32 v186, v177 offset:1088
	ds_read_b32 v187, v177 offset:1092
	ds_read_b32 v188, v177 offset:1096
	ds_read_b32 v189, v177 offset:1100
	ds_read_b32 v190, v177 offset:1120
	ds_read_b32 v191, v177 offset:1124
	ds_read_b32 v192, v177 offset:1128
	ds_read_b32 v193, v177 offset:1132
	ds_read_b32 v194, v177 offset:1152
	ds_read_b32 v195, v177 offset:1156
	ds_read_b32 v196, v177 offset:1160
	ds_read_b32 v197, v177 offset:1164
	ds_read_b32 v198, v177 offset:1184
	ds_read_b32 v199, v177 offset:1188
	ds_read_b32 v200, v177 offset:1192
	ds_read_b32 v201, v177 offset:1196
	ds_read_b32 v202, v177 offset:1216
	ds_read_b32 v203, v177 offset:1220
	ds_read_b32 v204, v177 offset:1224
	ds_read_b32 v205, v177 offset:1228
	ds_read_b32 v206, v177 offset:1248
	ds_read_b32 v207, v177 offset:1252
	ds_read_b32 v208, v177 offset:1256
	ds_read_b32 v209, v177 offset:1260
	s_waitcnt lgkmcnt(0)
	v_pk_add_f32 v[96:97], v[96:97], v[178:179]
	v_pk_add_f32 v[98:99], v[98:99], v[180:181]
	v_pk_add_f32 v[100:101], v[100:101], v[182:183]
	v_pk_add_f32 v[102:103], v[102:103], v[184:185]
	v_pk_add_f32 v[104:105], v[104:105], v[186:187]
	v_pk_add_f32 v[106:107], v[106:107], v[188:189]
	v_pk_add_f32 v[108:109], v[108:109], v[190:191]
	v_pk_add_f32 v[110:111], v[110:111], v[192:193]
	v_pk_add_f32 v[80:81], v[80:81], v[194:195]
	v_pk_add_f32 v[82:83], v[82:83], v[196:197]
	v_pk_add_f32 v[84:85], v[84:85], v[198:199]
	v_pk_add_f32 v[86:87], v[86:87], v[200:201]
	v_pk_add_f32 v[88:89], v[88:89], v[202:203]
	v_pk_add_f32 v[90:91], v[90:91], v[204:205]
	v_pk_add_f32 v[92:93], v[92:93], v[206:207]
	v_pk_add_f32 v[94:95], v[94:95], v[208:209]

.LBB0_216:
	s_cmpk_gt_u32 s2, 0xff
	s_waitcnt lgkmcnt(0)
	s_barrier
	s_cbranch_scc1 .LBB0_218
	ds_read2st64_b32 v[10:11], v4 offset1:1
	ds_read2st64_b32 v[12:13], v4 offset0:2 offset1:3
	ds_read2st64_b32 v[14:15], v4 offset0:4 offset1:5
	ds_read2st64_b32 v[26:27], v4 offset0:6 offset1:7
	ds_read2st64_b32 v[28:29], v4 offset0:8 offset1:9
	ds_read2st64_b32 v[30:31], v4 offset0:10 offset1:11
	ds_read2st64_b32 v[86:87], v4 offset0:12 offset1:13
	ds_read2st64_b32 v[88:89], v4 offset0:14 offset1:15
	ds_read2st64_b32 v[90:91], v4 offset0:16 offset1:17
	ds_read2st64_b32 v[92:93], v4 offset0:18 offset1:19
	ds_read2st64_b32 v[94:95], v4 offset0:20 offset1:21
	ds_read2st64_b32 v[96:97], v4 offset0:22 offset1:23
	ds_read2st64_b32 v[98:99], v4 offset0:24 offset1:25
	ds_read2st64_b32 v[100:101], v4 offset0:26 offset1:27
	ds_read2st64_b32 v[102:103], v4 offset0:28 offset1:29
	ds_read2st64_b32 v[104:105], v4 offset0:30 offset1:31
	ds_read2st64_b32 v[106:107], v4 offset0:32 offset1:33
	ds_read2st64_b32 v[108:109], v4 offset0:34 offset1:35
	ds_read2st64_b32 v[110:111], v4 offset0:36 offset1:37
	ds_read2st64_b32 v[112:113], v4 offset0:38 offset1:39
	ds_read2st64_b32 v[114:115], v4 offset0:40 offset1:41
	ds_read2st64_b32 v[116:117], v4 offset0:42 offset1:43
	ds_read2st64_b32 v[118:119], v4 offset0:44 offset1:45
	ds_read2st64_b32 v[120:121], v4 offset0:46 offset1:47
	ds_read2st64_b32 v[122:123], v4 offset0:48 offset1:49
	ds_read2st64_b32 v[124:125], v4 offset0:50 offset1:51
	ds_read2st64_b32 v[126:127], v4 offset0:52 offset1:53
	s_waitcnt vmcnt(3)
	ds_read2st64_b32 v[128:129], v4 offset0:54 offset1:55
	ds_read2st64_b32 v[130:131], v4 offset0:56 offset1:57
	s_waitcnt vmcnt(2)
	ds_read2st64_b32 v[132:133], v4 offset0:58 offset1:59
	ds_read2st64_b32 v[78:79], v4 offset0:60 offset1:61
	ds_read2st64_b32 v[4:5], v4 offset0:62 offset1:63
	s_waitcnt lgkmcnt(14)
	v_pk_fma_f32 v[70:71], v[174:175], v[10:11], v[70:71] neg_lo:[1,0,0] neg_hi:[1,0,0]
	v_lshlrev_b32_e32 v80, 2, v151
	v_pk_fma_f32 v[76:77], v[174:175], v[12:13], v[76:77] neg_lo:[1,0,0] neg_hi:[1,0,0]
	s_waitcnt vmcnt(1)
	v_pk_mul_f32 v[138:139], v[70:71], v[70:71]
	v_lshlrev_b32_e32 v168, 11, v150
	global_load_dwordx4 v[82:85], v80, s[4:5]
	global_load_dwordx4 v[176:179], v80, s[4:5] offset:32
	global_load_dwordx4 v[180:183], v80, s[4:5] offset:64
	global_load_dwordx4 v[184:187], v80, s[4:5] offset:96
	global_load_dwordx4 v[188:191], v80, s[4:5] offset:128
	global_load_dwordx4 v[192:195], v80, s[4:5] offset:160
	global_load_dwordx4 v[196:199], v80, s[4:5] offset:192
	global_load_dwordx4 v[200:203], v80, s[4:5] offset:224
	global_load_dwordx4 v[204:207], v80, s[4:5] offset:256
	global_load_dwordx4 v[208:211], v80, s[4:5] offset:288
	global_load_dwordx4 v[212:215], v80, s[4:5] offset:320
	global_load_dwordx4 v[244:247], v80, s[4:5] offset:352
	global_load_dwordx4 v[248:251], v80, s[4:5] offset:384
	v_pk_mul_f32 v[136:137], v[76:77], v[76:77]
	v_add_f32_e32 v81, v138, v139
	s_waitcnt lgkmcnt(0)
	v_pk_fma_f32 v[4:5], v[174:175], v[4:5], v[2:3] neg_lo:[1,0,0] neg_hi:[1,0,0]
	v_lshl_add_u64 v[2:3], s[58:59], 0, v[168:169]
	v_mov_b32_e32 v145, v169
	s_waitcnt vmcnt(13)
	v_pk_fma_f32 v[142:143], v[174:175], v[14:15], v[66:67] neg_lo:[1,0,0] neg_hi:[1,0,0]
	v_add_f32_e32 v81, v81, v136
	v_lshl_add_u64 v[2:3], v[2:3], 0, v[144:145]
	v_pk_mul_f32 v[144:145], v[142:143], v[142:143]
	v_add_f32_e32 v81, v81, v137
	v_pk_fma_f32 v[74:75], v[174:175], v[26:27], v[74:75] neg_lo:[1,0,0] neg_hi:[1,0,0]
	v_add_f32_e32 v81, v81, v144
	v_pk_mul_f32 v[140:141], v[74:75], v[74:75]
	v_add_f32_e32 v81, v81, v145
	v_pk_fma_f32 v[148:149], v[174:175], v[28:29], v[64:65] neg_lo:[1,0,0] neg_hi:[1,0,0]
	v_add_f32_e32 v81, v81, v140
	v_lshlrev_b32_e32 v168, 1, v151
	v_pk_mul_f32 v[150:151], v[148:149], v[148:149]
	v_add_f32_e32 v81, v81, v141
	v_pk_fma_f32 v[72:73], v[174:175], v[30:31], v[72:73] neg_lo:[1,0,0] neg_hi:[1,0,0]
	v_add_f32_e32 v81, v81, v150
	v_pk_mul_f32 v[146:147], v[72:73], v[72:73]
	v_add_f32_e32 v81, v81, v151
	v_pk_fma_f32 v[86:87], v[174:175], v[86:87], v[58:59] neg_lo:[1,0,0] neg_hi:[1,0,0]
	v_add_f32_e32 v81, v81, v146
	v_pk_fma_f32 v[66:67], v[174:175], v[88:89], v[68:69] neg_lo:[1,0,0] neg_hi:[1,0,0]
	v_pk_mul_f32 v[88:89], v[86:87], v[86:87]
	v_add_f32_e32 v81, v81, v147
	v_add_f32_e32 v81, v81, v88
	v_pk_mul_f32 v[68:69], v[66:67], v[66:67]
	v_add_f32_e32 v81, v81, v89
	v_pk_fma_f32 v[64:65], v[174:175], v[90:91], v[52:53] neg_lo:[1,0,0] neg_hi:[1,0,0]
	v_add_f32_e32 v68, v81, v68
	v_pk_mul_f32 v[90:91], v[64:65], v[64:65]
	v_add_f32_e32 v68, v68, v69
	v_pk_fma_f32 v[62:63], v[174:175], v[92:93], v[62:63] neg_lo:[1,0,0] neg_hi:[1,0,0]
	v_add_f32_e32 v68, v68, v90
	v_pk_mul_f32 v[92:93], v[62:63], v[62:63]
	v_add_f32_e32 v68, v68, v91
	v_pk_fma_f32 v[58:59], v[174:175], v[96:97], v[60:61] neg_lo:[1,0,0] neg_hi:[1,0,0]
	v_pk_fma_f32 v[60:61], v[174:175], v[94:95], v[50:51] neg_lo:[1,0,0] neg_hi:[1,0,0]
	v_add_f32_e32 v68, v68, v92
	v_pk_mul_f32 v[94:95], v[60:61], v[60:61]
	v_add_f32_e32 v68, v68, v93
	v_add_f32_e32 v68, v68, v94
	v_pk_mul_f32 v[96:97], v[58:59], v[58:59]
	v_add_f32_e32 v68, v68, v95
	v_pk_fma_f32 v[52:53], v[174:175], v[100:101], v[56:57] neg_lo:[1,0,0] neg_hi:[1,0,0]
	v_pk_fma_f32 v[56:57], v[174:175], v[98:99], v[48:49] neg_lo:[1,0,0] neg_hi:[1,0,0]
	v_add_f32_e32 v68, v68, v96
	v_pk_mul_f32 v[98:99], v[56:57], v[56:57]
	v_add_f32_e32 v68, v68, v97
	v_add_f32_e32 v68, v68, v98
	v_pk_mul_f32 v[100:101], v[52:53], v[52:53]
	v_add_f32_e32 v68, v68, v99
	v_pk_fma_f32 v[50:51], v[174:175], v[102:103], v[32:33] neg_lo:[1,0,0] neg_hi:[1,0,0]
	v_add_f32_e32 v68, v68, v100
	v_pk_mul_f32 v[102:103], v[50:51], v[50:51]
	v_add_f32_e32 v68, v68, v101
	v_pk_fma_f32 v[48:49], v[174:175], v[104:105], v[54:55] neg_lo:[1,0,0] neg_hi:[1,0,0]
	v_add_f32_e32 v68, v68, v102
	v_pk_mul_f32 v[54:55], v[48:49], v[48:49]
	v_add_f32_e32 v68, v68, v103
	v_pk_fma_f32 v[40:41], v[174:175], v[106:107], v[40:41] neg_lo:[1,0,0] neg_hi:[1,0,0]
	v_add_f32_e32 v54, v68, v54
	v_pk_mul_f32 v[104:105], v[40:41], v[40:41]
	v_add_f32_e32 v54, v54, v55
	v_pk_fma_f32 v[32:33], v[174:175], v[108:109], v[46:47] neg_lo:[1,0,0] neg_hi:[1,0,0]
	v_add_f32_e32 v54, v54, v104
	v_pk_mul_f32 v[46:47], v[32:33], v[32:33]
	v_add_f32_e32 v54, v54, v105
	v_pk_fma_f32 v[30:31], v[174:175], v[110:111], v[38:39] neg_lo:[1,0,0] neg_hi:[1,0,0]
	v_add_f32_e32 v46, v54, v46
	v_pk_mul_f32 v[38:39], v[30:31], v[30:31]
	v_add_f32_e32 v46, v46, v47
	v_pk_fma_f32 v[28:29], v[174:175], v[112:113], v[44:45] neg_lo:[1,0,0] neg_hi:[1,0,0]
	v_add_f32_e32 v38, v46, v38
	v_pk_mul_f32 v[44:45], v[28:29], v[28:29]
	v_add_f32_e32 v38, v38, v39
	v_pk_fma_f32 v[26:27], v[174:175], v[114:115], v[18:19] neg_lo:[1,0,0] neg_hi:[1,0,0]
	v_add_f32_e32 v38, v38, v44
	v_pk_mul_f32 v[108:109], v[26:27], v[26:27]
	v_add_f32_e32 v38, v38, v45
	v_pk_fma_f32 v[22:23], v[174:175], v[116:117], v[22:23] neg_lo:[1,0,0] neg_hi:[1,0,0]
	v_add_f32_e32 v38, v38, v108
	v_pk_mul_f32 v[106:107], v[22:23], v[22:23]
	v_add_f32_e32 v38, v38, v109
	v_pk_fma_f32 v[20:21], v[174:175], v[118:119], v[20:21] neg_lo:[1,0,0] neg_hi:[1,0,0]
	v_add_f32_e32 v38, v38, v106
	v_pk_mul_f32 v[110:111], v[20:21], v[20:21]
	v_add_f32_e32 v38, v38, v107
	v_pk_fma_f32 v[18:19], v[174:175], v[120:121], v[42:43] neg_lo:[1,0,0] neg_hi:[1,0,0]
	v_add_f32_e32 v38, v38, v110
	v_pk_mul_f32 v[42:43], v[18:19], v[18:19]
	v_add_f32_e32 v38, v38, v111
	v_pk_fma_f32 v[16:17], v[174:175], v[122:123], v[16:17] neg_lo:[1,0,0] neg_hi:[1,0,0]
	v_add_f32_e32 v38, v38, v42
	v_pk_mul_f32 v[112:113], v[16:17], v[16:17]
	v_add_f32_e32 v38, v38, v43
	v_pk_fma_f32 v[14:15], v[174:175], v[124:125], v[36:37] neg_lo:[1,0,0] neg_hi:[1,0,0]
	v_add_f32_e32 v38, v38, v112
	v_pk_mul_f32 v[36:37], v[14:15], v[14:15]
	v_add_f32_e32 v38, v38, v113
	v_pk_fma_f32 v[12:13], v[174:175], v[126:127], v[24:25] neg_lo:[1,0,0] neg_hi:[1,0,0]
	v_add_f32_e32 v36, v38, v36
	v_pk_mul_f32 v[24:25], v[12:13], v[12:13]
	v_add_f32_e32 v36, v36, v37
	v_pk_fma_f32 v[10:11], v[174:175], v[128:129], v[34:35] neg_lo:[1,0,0] neg_hi:[1,0,0]
	v_add_f32_e32 v24, v36, v24
	v_pk_mul_f32 v[34:35], v[10:11], v[10:11]
	v_add_f32_e32 v24, v24, v25
	v_pk_fma_f32 v[8:9], v[174:175], v[130:131], v[8:9] neg_lo:[1,0,0] neg_hi:[1,0,0]
	v_add_f32_e32 v24, v24, v34
	v_pk_mul_f32 v[116:117], v[8:9], v[8:9]
	v_add_f32_e32 v24, v24, v35
	v_pk_fma_f32 v[6:7], v[174:175], v[132:133], v[6:7] neg_lo:[1,0,0] neg_hi:[1,0,0]
	v_add_f32_e32 v24, v24, v116
	v_pk_mul_f32 v[114:115], v[6:7], v[6:7]
	v_add_f32_e32 v24, v24, v117
	v_pk_fma_f32 v[0:1], v[174:175], v[78:79], v[0:1] neg_lo:[1,0,0] neg_hi:[1,0,0]
	v_add_f32_e32 v24, v24, v114
	v_pk_mul_f32 v[78:79], v[0:1], v[0:1]
	v_add_f32_e32 v24, v24, v115
	v_add_f32_e32 v24, v24, v78
	v_pk_mul_f32 v[134:135], v[4:5], v[4:5]
	v_add_f32_e32 v24, v24, v79
	v_add_f32_e32 v24, v24, v134
	v_add_f32_e32 v24, v24, v135
	ds_bpermute_b32 v25, v155, v24
	v_lshl_add_u64 v[2:3], v[2:3], 0, v[168:169]
	s_waitcnt lgkmcnt(0)
	v_add_f32_e32 v24, v24, v25
	v_fmamk_f32 v24, v24, 0x3c000000, v236
	v_cmp_gt_f32_e32 vcc, s39, v24
	v_mul_f32_e32 v25, 0x4b800000, v24
	s_nop 0
	v_cndmask_b32_e32 v24, v24, v25, vcc
	v_rsq_f32_e32 v24, v24
	s_nop 0
	v_mul_f32_e32 v25, 0x45800000, v24
	v_cndmask_b32_e32 v24, v24, v25, vcc
	v_mul_f32_e32 v24, v242, v24
	v_pk_mul_f32 v[34:35], v[70:71], v[24:25] op_sel_hi:[1,0]
	v_pk_mul_f32 v[36:37], v[76:77], v[24:25] op_sel_hi:[1,0]
	s_waitcnt vmcnt(0)
	v_pk_mul_f32 v[34:35], v[82:83], v[34:35]
	v_pk_mul_f32 v[36:37], v[84:85], v[36:37]
	v_cvt_pk_bf16_f32 v34, v34, v35
	v_cvt_pk_bf16_f32 v35, v36, v37
	global_store_dwordx2 v[2:3], v[34:35], off
	v_mov_b64_e32 v[34:35], v[176:177]
	v_mov_b64_e32 v[36:37], v[178:179]
	global_load_dwordx4 v[176:179], v80, s[4:5] offset:416
	v_pk_mul_f32 v[38:39], v[142:143], v[24:25] op_sel_hi:[1,0]
	v_pk_mul_f32 v[32:33], v[32:33], v[24:25] op_sel_hi:[1,0]
	v_pk_mul_f32 v[30:31], v[30:31], v[24:25] op_sel_hi:[1,0]
	v_pk_mul_f32 v[28:29], v[28:29], v[24:25] op_sel_hi:[1,0]
	v_pk_mul_f32 v[26:27], v[26:27], v[24:25] op_sel_hi:[1,0]
	v_pk_mul_f32 v[22:23], v[22:23], v[24:25] op_sel_hi:[1,0]
	v_pk_mul_f32 v[20:21], v[20:21], v[24:25] op_sel_hi:[1,0]
	v_pk_mul_f32 v[18:19], v[18:19], v[24:25] op_sel_hi:[1,0]
	v_pk_mul_f32 v[16:17], v[16:17], v[24:25] op_sel_hi:[1,0]
	v_pk_mul_f32 v[14:15], v[14:15], v[24:25] op_sel_hi:[1,0]
	v_pk_mul_f32 v[12:13], v[12:13], v[24:25] op_sel_hi:[1,0]
	v_pk_mul_f32 v[10:11], v[10:11], v[24:25] op_sel_hi:[1,0]
	v_pk_mul_f32 v[8:9], v[8:9], v[24:25] op_sel_hi:[1,0]
	v_pk_mul_f32 v[6:7], v[6:7], v[24:25] op_sel_hi:[1,0]
	v_pk_mul_f32 v[0:1], v[0:1], v[24:25] op_sel_hi:[1,0]
	v_pk_mul_f32 v[4:5], v[4:5], v[24:25] op_sel_hi:[1,0]
	v_pk_mul_f32 v[34:35], v[34:35], v[38:39]
	v_pk_mul_f32 v[38:39], v[74:75], v[24:25] op_sel_hi:[1,0]
	v_cvt_pk_bf16_f32 v34, v34, v35
	v_pk_mul_f32 v[36:37], v[36:37], v[38:39]
	v_pk_mul_f32 v[38:39], v[148:149], v[24:25] op_sel_hi:[1,0]
	v_cvt_pk_bf16_f32 v35, v36, v37
	global_store_dwordx2 v[2:3], v[34:35], off offset:16
	v_mov_b64_e32 v[34:35], v[180:181]
	v_mov_b64_e32 v[36:37], v[182:183]
	global_load_dwordx4 v[180:183], v80, s[4:5] offset:448
	v_pk_mul_f32 v[34:35], v[34:35], v[38:39]
	v_pk_mul_f32 v[38:39], v[72:73], v[24:25] op_sel_hi:[1,0]
	v_cvt_pk_bf16_f32 v34, v34, v35
	v_pk_mul_f32 v[36:37], v[36:37], v[38:39]
	v_pk_mul_f32 v[38:39], v[86:87], v[24:25] op_sel_hi:[1,0]
	v_cvt_pk_bf16_f32 v35, v36, v37
	global_store_dwordx2 v[2:3], v[34:35], off offset:32
	v_mov_b64_e32 v[34:35], v[184:185]
	v_mov_b64_e32 v[36:37], v[186:187]
	global_load_dwordx4 v[184:187], v80, s[4:5] offset:480
	v_pk_mul_f32 v[34:35], v[34:35], v[38:39]
	v_pk_mul_f32 v[38:39], v[66:67], v[24:25] op_sel_hi:[1,0]
	v_cvt_pk_bf16_f32 v34, v34, v35
	v_pk_mul_f32 v[36:37], v[36:37], v[38:39]
	v_pk_mul_f32 v[38:39], v[64:65], v[24:25] op_sel_hi:[1,0]
	v_cvt_pk_bf16_f32 v35, v36, v37
	global_store_dwordx2 v[2:3], v[34:35], off offset:48
	v_mov_b64_e32 v[34:35], v[188:189]
	v_mov_b64_e32 v[36:37], v[190:191]
	v_pk_mul_f32 v[34:35], v[34:35], v[38:39]
	v_pk_mul_f32 v[38:39], v[62:63], v[24:25] op_sel_hi:[1,0]
	v_cvt_pk_bf16_f32 v34, v34, v35
	v_pk_mul_f32 v[36:37], v[36:37], v[38:39]
	v_pk_mul_f32 v[38:39], v[60:61], v[24:25] op_sel_hi:[1,0]
	v_cvt_pk_bf16_f32 v35, v36, v37
	global_store_dwordx2 v[2:3], v[34:35], off offset:64
	v_mov_b64_e32 v[34:35], v[192:193]
	v_mov_b64_e32 v[36:37], v[194:195]
	v_pk_mul_f32 v[34:35], v[34:35], v[38:39]
	v_pk_mul_f32 v[38:39], v[58:59], v[24:25] op_sel_hi:[1,0]
	v_cvt_pk_bf16_f32 v34, v34, v35
	v_pk_mul_f32 v[36:37], v[36:37], v[38:39]
	v_pk_mul_f32 v[38:39], v[56:57], v[24:25] op_sel_hi:[1,0]
	v_cvt_pk_bf16_f32 v35, v36, v37
	global_store_dwordx2 v[2:3], v[34:35], off offset:80
	v_mov_b64_e32 v[34:35], v[196:197]
	v_mov_b64_e32 v[36:37], v[198:199]
	v_pk_mul_f32 v[34:35], v[34:35], v[38:39]
	v_pk_mul_f32 v[38:39], v[52:53], v[24:25] op_sel_hi:[1,0]
	v_cvt_pk_bf16_f32 v34, v34, v35
	v_pk_mul_f32 v[36:37], v[36:37], v[38:39]
	v_pk_mul_f32 v[38:39], v[50:51], v[24:25] op_sel_hi:[1,0]
	v_cvt_pk_bf16_f32 v35, v36, v37
	global_store_dwordx2 v[2:3], v[34:35], off offset:96
	v_mov_b64_e32 v[34:35], v[200:201]
	v_mov_b64_e32 v[36:37], v[202:203]
	v_pk_mul_f32 v[34:35], v[38:39], v[34:35]
	v_pk_mul_f32 v[38:39], v[48:49], v[24:25] op_sel_hi:[1,0]
	v_cvt_pk_bf16_f32 v34, v34, v35
	v_pk_mul_f32 v[36:37], v[38:39], v[36:37]
	v_pk_mul_f32 v[38:39], v[40:41], v[24:25] op_sel_hi:[1,0]
	v_cvt_pk_bf16_f32 v35, v36, v37
	global_store_dwordx2 v[2:3], v[34:35], off offset:112
	v_mov_b64_e32 v[34:35], v[204:205]
	v_mov_b64_e32 v[36:37], v[206:207]
	v_pk_mul_f32 v[34:35], v[38:39], v[34:35]
	v_pk_mul_f32 v[32:33], v[32:33], v[36:37]
	v_cvt_pk_bf16_f32 v34, v34, v35
	v_cvt_pk_bf16_f32 v35, v32, v33
	global_store_dwordx2 v[2:3], v[34:35], off offset:128
	v_mov_b64_e32 v[32:33], v[208:209]
	v_mov_b64_e32 v[34:35], v[210:211]
	v_pk_mul_f32 v[30:31], v[30:31], v[32:33]
	v_pk_mul_f32 v[28:29], v[28:29], v[34:35]
	v_cvt_pk_bf16_f32 v30, v30, v31
	v_cvt_pk_bf16_f32 v31, v28, v29
	global_store_dwordx2 v[2:3], v[30:31], off offset:144
	v_mov_b64_e32 v[28:29], v[212:213]
	v_mov_b64_e32 v[30:31], v[214:215]
	v_pk_mul_f32 v[26:27], v[26:27], v[28:29]
	v_pk_mul_f32 v[22:23], v[22:23], v[30:31]
	v_cvt_pk_bf16_f32 v26, v26, v27
	v_cvt_pk_bf16_f32 v27, v22, v23
	global_store_dwordx2 v[2:3], v[26:27], off offset:160
	v_mov_b64_e32 v[26:27], v[244:245]
	v_mov_b64_e32 v[28:29], v[246:247]
	v_pk_mul_f32 v[20:21], v[20:21], v[26:27]
	v_pk_mul_f32 v[18:19], v[18:19], v[28:29]
	v_cvt_pk_bf16_f32 v20, v20, v21
	v_cvt_pk_bf16_f32 v21, v18, v19
	global_store_dwordx2 v[2:3], v[20:21], off offset:176
	v_mov_b64_e32 v[18:19], v[248:249]
	v_mov_b64_e32 v[20:21], v[250:251]
	v_pk_mul_f32 v[16:17], v[16:17], v[18:19]
	v_pk_mul_f32 v[14:15], v[14:15], v[20:21]
	v_cvt_pk_bf16_f32 v16, v16, v17
	v_cvt_pk_bf16_f32 v17, v14, v15
	global_store_dwordx2 v[2:3], v[16:17], off offset:192
	s_waitcnt vmcnt(14)
	v_mov_b64_e32 v[14:15], v[176:177]
	v_mov_b64_e32 v[16:17], v[178:179]
	v_pk_mul_f32 v[12:13], v[12:13], v[14:15]
	v_pk_mul_f32 v[10:11], v[10:11], v[16:17]
	v_cvt_pk_bf16_f32 v12, v12, v13
	v_cvt_pk_bf16_f32 v13, v10, v11
	global_store_dwordx2 v[2:3], v[12:13], off offset:208
	s_waitcnt vmcnt(13)
	v_mov_b64_e32 v[10:11], v[180:181]
	v_mov_b64_e32 v[12:13], v[182:183]
	v_pk_mul_f32 v[8:9], v[8:9], v[10:11]
	v_pk_mul_f32 v[6:7], v[6:7], v[12:13]
	v_cvt_pk_bf16_f32 v8, v8, v9
	v_cvt_pk_bf16_f32 v9, v6, v7
	global_store_dwordx2 v[2:3], v[8:9], off offset:224
	s_waitcnt vmcnt(12)
	v_mov_b64_e32 v[6:7], v[184:185]
	v_mov_b64_e32 v[8:9], v[186:187]
	v_pk_mul_f32 v[0:1], v[0:1], v[6:7]
	v_pk_mul_f32 v[4:5], v[4:5], v[8:9]
	v_cvt_pk_bf16_f32 v0, v0, v1
	v_cvt_pk_bf16_f32 v1, v4, v5
	global_store_dwordx2 v[2:3], v[0:1], off offset:240
